# residual-GEMM epilogues: lane^16 row-sum exchange by v_permlane16_swap instead of ds_bpermute + lgkmcnt wait (64 sites)
# baseline (speedup 1.0000x reference)
; __device__ __forceinline__ void store16_wt(void* p, wt_u32x4 v) { asm volatile("global_store_dwordx4 %0, %1, off sc1\n\ts_nop 1" :: "v"(p), "v"(v) : "memory"); }
; __device__ __forceinline__ float lane_get(float v, int src_lane) { return __builtin_bit_cast(float, __builtin_amdgcn_ds_bpermute(src_lane << 2, __builtin_bit_cast(int, v))); }
; __device__ __forceinline__ unsigned cvt_pk_bf16(float lo, float hi) { unsigned r; asm volatile("v_cvt_pk_bf16_f32 %0, %1, %2" : "=v"(r) : "v"(lo), "v"(hi)); return r; }
;     __device__ __forceinline__ void operator()(const f32x4 (&acc)[2][2][4][2], const Unit& u, int wr, int wc, int fr, int fq, int ui) const {
;     ...
;         const int row0 = u.pm * BM + wr * 64 + fr, col0 = u.pn * BM + wc * 32 + 8 * fq, lane = fq * 16 + fr;
; #pragma unroll
;         for (int ai = 0; ai < 2; ++ai)
; #pragma unroll
;             for (int m = 0; m < 4; ++m) { const int row = row0 + ai * HALF + m * 16; bf16_t* rowb = XB + (size_t)row * ldc + col0; float ss = 0.f;
; #pragma unroll
;                 for (int bj = 0; bj < 2; ++bj) { const f32x4 x0 = acc[ai][bj][m][0], x1 = acc[ai][bj][m][1];
;                     ss += ((x0[0] * x0[0] + x0[1] * x0[1]) + (x0[2] * x0[2] + x0[3] * x0[3])) + ((x1[0] * x1[0] + x1[1] * x1[1]) + (x1[2] * x1[2] + x1[3] * x1[3]));
;                     u32x4 w; w.x = cvt_pk_bf16(x0[0], x0[1]); w.y = cvt_pk_bf16(x0[2], x0[3]); w.z = cvt_pk_bf16(x1[0], x1[1]); w.w = cvt_pk_bf16(x1[2], x1[3]); store16_wt(rowb + bj * HALF, w); }
;                 ss += lane_get(ss, lane ^ 16); ss += lane_get(ss, lane ^ 32);
;                 if (fq == 0) __hip_atomic_store((unsigned*)stats + (size_t)row * 16 + u.pn * 4 + wc, __float_as_uint(ss), __ATOMIC_RELAXED, __HIP_MEMORY_SCOPE_AGENT); }
.LBB0_300:
	v_lshl_add_u32 v146, s70, 8, v148
	v_lshl_or_b32 v144, s69, 8, v152
	v_ashrrev_i32_e32 v145, 31, v144
	v_ashrrev_i32_e32 v147, 31, v146
	v_mul_f32_e32 v156, v113, v113
	v_lshl_add_u64 v[144:145], v[144:145], 1, s[10:11]
	v_lshlrev_b64 v[154:155], 11, v[146:147]
	v_fmac_f32_e32 v156, v112, v112
	v_mul_f32_e32 v157, v115, v115
	v_cvt_pk_bf16_f32 v112, v112, v113
	v_cvt_pk_bf16_f32 v113, v114, v115
	v_lshl_add_u64 v[154:155], v[144:145], 0, v[154:155]
	v_fmac_f32_e32 v157, v114, v114
	v_cvt_pk_bf16_f32 v114, v120, v121
	v_cvt_pk_bf16_f32 v115, v122, v123
	v_add_f32_e32 v156, v156, v157
	global_store_dwordx4 v[154:155], v[112:115], off sc1
	s_nop 1
	v_mul_f32_e32 v112, v117, v117
	v_mul_f32_e32 v113, v119, v119
	v_fmac_f32_e32 v112, v116, v116
	v_fmac_f32_e32 v113, v118, v118
	v_mul_f32_e32 v157, v121, v121
	v_mul_f32_e32 v158, v123, v123
	v_add_f32_e32 v112, v112, v113
	v_mul_f32_e32 v113, v125, v125
	v_mul_f32_e32 v114, v127, v127
	v_fmac_f32_e32 v157, v120, v120
	v_fmac_f32_e32 v158, v122, v122
	v_fmac_f32_e32 v113, v124, v124
	v_fmac_f32_e32 v114, v126, v126
	v_add_f32_e32 v157, v157, v158
	v_add_f32_e32 v113, v113, v114
	v_add_f32_e32 v156, v156, v157
	v_add_f32_e32 v112, v112, v113
	v_add_f32_e32 v112, v156, v112
	v_mov_b32_e32 v113, v112
	s_nop 1
	v_permlane16_swap_b32_e32 v113, v112
	s_lshl_b32 s30, s69, 2
	s_ashr_i32 s31, s30, 31
	s_lshl_b64 s[30:31], s[30:31], 2
	v_cvt_pk_bf16_f32 v114, v116, v117
	s_waitcnt lgkmcnt(0)
	v_add_f32_e32 v112, v112, v113
	ds_bpermute_b32 v113, v151, v112
	v_cvt_pk_bf16_f32 v115, v118, v119
	v_cvt_pk_bf16_f32 v116, v124, v125
	v_cvt_pk_bf16_f32 v117, v126, v127
	v_lshl_add_u64 v[118:119], v[154:155], 0, s[26:27]
	global_store_dwordx4 v[118:119], v[114:117], off sc1
	s_nop 1
	s_add_u32 s30, s62, s30
	s_addc_u32 s31, s63, s31
	s_and_saveexec_b64 s[34:35], s[2:3]
	s_cbranch_execz .LBB0_302
	v_lshlrev_b64 v[114:115], 6, v[146:147]
	v_lshl_add_u64 v[114:115], s[30:31], 0, v[114:115]
	s_waitcnt lgkmcnt(0)
	v_add_f32_e32 v112, v112, v113
	global_store_dword v[114:115], v112, off sc1
.LBB0_302:
	s_or_b64 exec, exec, s[34:35]
	v_or_b32_e32 v112, 16, v146
	s_waitcnt lgkmcnt(0)
	v_ashrrev_i32_e32 v113, 31, v112
	v_mul_f32_e32 v116, v97, v97
	v_lshlrev_b64 v[114:115], 11, v[112:113]
	v_fmac_f32_e32 v116, v96, v96
	v_mul_f32_e32 v117, v99, v99
	v_cvt_pk_bf16_f32 v96, v96, v97
	v_cvt_pk_bf16_f32 v97, v98, v99
	v_lshl_add_u64 v[114:115], v[144:145], 0, v[114:115]
	v_fmac_f32_e32 v117, v98, v98
	v_cvt_pk_bf16_f32 v98, v104, v105
	v_cvt_pk_bf16_f32 v99, v106, v107
	v_add_f32_e32 v116, v116, v117
	global_store_dwordx4 v[114:115], v[96:99], off sc1
	s_nop 1
	v_mul_f32_e32 v96, v101, v101
	v_mul_f32_e32 v97, v103, v103
	v_fmac_f32_e32 v96, v100, v100
	v_fmac_f32_e32 v97, v102, v102
	v_mul_f32_e32 v117, v105, v105
	v_mul_f32_e32 v118, v107, v107
	v_add_f32_e32 v96, v96, v97
	v_mul_f32_e32 v97, v109, v109
	v_mul_f32_e32 v98, v111, v111
	v_fmac_f32_e32 v117, v104, v104
	v_fmac_f32_e32 v118, v106, v106
	v_fmac_f32_e32 v97, v108, v108
	v_fmac_f32_e32 v98, v110, v110
	v_add_f32_e32 v117, v117, v118
	v_add_f32_e32 v97, v97, v98
	v_add_f32_e32 v116, v116, v117
	v_add_f32_e32 v96, v96, v97
	v_add_f32_e32 v96, v116, v96
	v_mov_b32_e32 v97, v96
	s_nop 1
	v_permlane16_swap_b32_e32 v97, v96
	v_cvt_pk_bf16_f32 v98, v100, v101
	v_cvt_pk_bf16_f32 v99, v102, v103
	v_cvt_pk_bf16_f32 v100, v108, v109
	v_cvt_pk_bf16_f32 v101, v110, v111
	s_waitcnt lgkmcnt(0)
	v_add_f32_e32 v96, v96, v97
	ds_bpermute_b32 v97, v151, v96
	v_lshl_add_u64 v[102:103], v[114:115], 0, s[26:27]
	global_store_dwordx4 v[102:103], v[98:101], off sc1
	s_nop 1
	s_and_saveexec_b64 s[34:35], s[2:3]
	s_cbranch_execz .LBB0_304
	v_lshlrev_b64 v[98:99], 6, v[112:113]
	v_lshl_add_u64 v[98:99], s[30:31], 0, v[98:99]
	s_waitcnt lgkmcnt(0)
	v_add_f32_e32 v96, v96, v97
	global_store_dword v[98:99], v96, off sc1
.LBB0_304:
	s_or_b64 exec, exec, s[34:35]
	v_or_b32_e32 v96, 32, v146
	s_waitcnt lgkmcnt(0)
	v_ashrrev_i32_e32 v97, 31, v96
	v_mul_f32_e32 v100, v81, v81
	v_lshlrev_b64 v[98:99], 11, v[96:97]
	v_fmac_f32_e32 v100, v80, v80
	v_mul_f32_e32 v101, v83, v83
	v_cvt_pk_bf16_f32 v80, v80, v81
	v_cvt_pk_bf16_f32 v81, v82, v83
	v_lshl_add_u64 v[98:99], v[144:145], 0, v[98:99]
	v_fmac_f32_e32 v101, v82, v82
	v_cvt_pk_bf16_f32 v82, v88, v89
	v_cvt_pk_bf16_f32 v83, v90, v91
	v_add_f32_e32 v100, v100, v101
	global_store_dwordx4 v[98:99], v[80:83], off sc1
	s_nop 1
	v_mul_f32_e32 v80, v85, v85
	v_mul_f32_e32 v81, v87, v87
	v_fmac_f32_e32 v80, v84, v84
	v_fmac_f32_e32 v81, v86, v86
	v_mul_f32_e32 v101, v89, v89
	v_mul_f32_e32 v102, v91, v91
	v_add_f32_e32 v80, v80, v81
	v_mul_f32_e32 v81, v93, v93
	v_mul_f32_e32 v82, v95, v95
	v_fmac_f32_e32 v101, v88, v88
	v_fmac_f32_e32 v102, v90, v90
	v_fmac_f32_e32 v81, v92, v92
	v_fmac_f32_e32 v82, v94, v94
	v_add_f32_e32 v101, v101, v102
	v_add_f32_e32 v81, v81, v82
	v_add_f32_e32 v100, v100, v101
	v_add_f32_e32 v80, v80, v81
	v_add_f32_e32 v80, v100, v80
	v_mov_b32_e32 v81, v80
	s_nop 1
	v_permlane16_swap_b32_e32 v81, v80
	v_cvt_pk_bf16_f32 v82, v84, v85
	v_cvt_pk_bf16_f32 v83, v86, v87
	v_cvt_pk_bf16_f32 v84, v92, v93
	v_cvt_pk_bf16_f32 v85, v94, v95
	s_waitcnt lgkmcnt(0)
	v_add_f32_e32 v80, v80, v81
	ds_bpermute_b32 v81, v151, v80
	v_lshl_add_u64 v[86:87], v[98:99], 0, s[26:27]
	global_store_dwordx4 v[86:87], v[82:85], off sc1
	s_nop 1
	s_and_saveexec_b64 s[34:35], s[2:3]
	s_cbranch_execz .LBB0_306
	v_lshlrev_b64 v[82:83], 6, v[96:97]
	v_lshl_add_u64 v[82:83], s[30:31], 0, v[82:83]
	s_waitcnt lgkmcnt(0)
	v_add_f32_e32 v80, v80, v81
	global_store_dword v[82:83], v80, off sc1
; __device__ __forceinline__ void store16_wt(void* p, wt_u32x4 v) { asm volatile("global_store_dwordx4 %0, %1, off sc1\n\ts_nop 1" :: "v"(p), "v"(v) : "memory"); }
; __device__ __forceinline__ float lane_get(float v, int src_lane) { return __builtin_bit_cast(float, __builtin_amdgcn_ds_bpermute(src_lane << 2, __builtin_bit_cast(int, v))); }
; __device__ __forceinline__ unsigned cvt_pk_bf16(float lo, float hi) { unsigned r; asm volatile("v_cvt_pk_bf16_f32 %0, %1, %2" : "=v"(r) : "v"(lo), "v"(hi)); return r; }
;     __device__ __forceinline__ void operator()(const f32x4 (&acc)[2][2][4][2], const Unit& u, int wr, int wc, int fr, int fq, int ui) const {
;     ...
;         const int row0 = u.pm * BM + wr * 64 + fr, col0 = u.pn * BM + wc * 32 + 8 * fq, lane = fq * 16 + fr;
; #pragma unroll
;         for (int ai = 0; ai < 2; ++ai)
; #pragma unroll
;             for (int m = 0; m < 4; ++m) { const int row = row0 + ai * HALF + m * 16; bf16_t* rowb = XB + (size_t)row * ldc + col0; float ss = 0.f;
; #pragma unroll
;                 for (int bj = 0; bj < 2; ++bj) { const f32x4 x0 = acc[ai][bj][m][0], x1 = acc[ai][bj][m][1];
;                     ss += ((x0[0] * x0[0] + x0[1] * x0[1]) + (x0[2] * x0[2] + x0[3] * x0[3])) + ((x1[0] * x1[0] + x1[1] * x1[1]) + (x1[2] * x1[2] + x1[3] * x1[3]));
;                     u32x4 w; w.x = cvt_pk_bf16(x0[0], x0[1]); w.y = cvt_pk_bf16(x0[2], x0[3]); w.z = cvt_pk_bf16(x1[0], x1[1]); w.w = cvt_pk_bf16(x1[2], x1[3]); store16_wt(rowb + bj * HALF, w); }
;                 ss += lane_get(ss, lane ^ 16); ss += lane_get(ss, lane ^ 32);
;                 if (fq == 0) __hip_atomic_store((unsigned*)stats + (size_t)row * 16 + u.pn * 4 + wc, __float_as_uint(ss), __ATOMIC_RELAXED, __HIP_MEMORY_SCOPE_AGENT); }
.LBB0_306:
	s_or_b64 exec, exec, s[34:35]
	v_or_b32_e32 v80, 48, v146
	s_waitcnt lgkmcnt(0)
	v_ashrrev_i32_e32 v81, 31, v80
	v_mul_f32_e32 v84, v65, v65
	v_lshlrev_b64 v[82:83], 11, v[80:81]
	v_fmac_f32_e32 v84, v64, v64
	v_mul_f32_e32 v85, v67, v67
	v_cvt_pk_bf16_f32 v64, v64, v65
	v_cvt_pk_bf16_f32 v65, v66, v67
	v_lshl_add_u64 v[82:83], v[144:145], 0, v[82:83]
	v_fmac_f32_e32 v85, v66, v66
	v_cvt_pk_bf16_f32 v66, v72, v73
	v_cvt_pk_bf16_f32 v67, v74, v75
	v_add_f32_e32 v84, v84, v85
	global_store_dwordx4 v[82:83], v[64:67], off sc1
	s_nop 1
	v_mul_f32_e32 v64, v69, v69
	v_mul_f32_e32 v65, v71, v71
	v_fmac_f32_e32 v64, v68, v68
	v_fmac_f32_e32 v65, v70, v70
	v_mul_f32_e32 v85, v73, v73
	v_mul_f32_e32 v86, v75, v75
	v_add_f32_e32 v64, v64, v65
	v_mul_f32_e32 v65, v77, v77
	v_mul_f32_e32 v66, v79, v79
	v_fmac_f32_e32 v85, v72, v72
	v_fmac_f32_e32 v86, v74, v74
	v_fmac_f32_e32 v65, v76, v76
	v_fmac_f32_e32 v66, v78, v78
	v_add_f32_e32 v85, v85, v86
	v_add_f32_e32 v65, v65, v66
	v_add_f32_e32 v84, v84, v85
	v_add_f32_e32 v64, v64, v65
	v_add_f32_e32 v64, v84, v64
	v_mov_b32_e32 v65, v64
	s_nop 1
	v_permlane16_swap_b32_e32 v65, v64
	v_cvt_pk_bf16_f32 v66, v68, v69
	v_cvt_pk_bf16_f32 v67, v70, v71
	v_cvt_pk_bf16_f32 v68, v76, v77
	v_cvt_pk_bf16_f32 v69, v78, v79
	s_waitcnt lgkmcnt(0)
	v_add_f32_e32 v64, v64, v65
	ds_bpermute_b32 v65, v151, v64
	v_lshl_add_u64 v[70:71], v[82:83], 0, s[26:27]
	global_store_dwordx4 v[70:71], v[66:69], off sc1
	s_nop 1
	s_and_saveexec_b64 s[34:35], s[2:3]
	s_cbranch_execz .LBB0_308
	v_lshlrev_b64 v[66:67], 6, v[80:81]
	v_lshl_add_u64 v[66:67], s[30:31], 0, v[66:67]
	s_waitcnt lgkmcnt(0)
	v_add_f32_e32 v64, v64, v65
	global_store_dword v[66:67], v64, off sc1
.LBB0_308:
	s_or_b64 exec, exec, s[34:35]
	v_add_u32_e32 v64, 0x80, v146
	s_waitcnt lgkmcnt(0)
	v_ashrrev_i32_e32 v65, 31, v64
	v_mul_f32_e32 v68, v49, v49
	v_lshlrev_b64 v[66:67], 11, v[64:65]
	v_fmac_f32_e32 v68, v48, v48
	v_mul_f32_e32 v69, v51, v51
	v_cvt_pk_bf16_f32 v48, v48, v49
	v_cvt_pk_bf16_f32 v49, v50, v51
	v_lshl_add_u64 v[66:67], v[144:145], 0, v[66:67]
	v_fmac_f32_e32 v69, v50, v50
	v_cvt_pk_bf16_f32 v50, v56, v57
	v_cvt_pk_bf16_f32 v51, v58, v59
	v_add_f32_e32 v68, v68, v69
	global_store_dwordx4 v[66:67], v[48:51], off sc1
	s_nop 1
	v_mul_f32_e32 v48, v53, v53
	v_mul_f32_e32 v49, v55, v55
	v_fmac_f32_e32 v48, v52, v52
	v_fmac_f32_e32 v49, v54, v54
	v_mul_f32_e32 v69, v57, v57
	v_mul_f32_e32 v70, v59, v59
	v_add_f32_e32 v48, v48, v49
	v_mul_f32_e32 v49, v61, v61
	v_mul_f32_e32 v50, v63, v63
	v_fmac_f32_e32 v69, v56, v56
	v_fmac_f32_e32 v70, v58, v58
	v_fmac_f32_e32 v49, v60, v60
	v_fmac_f32_e32 v50, v62, v62
	v_add_f32_e32 v69, v69, v70
	v_add_f32_e32 v49, v49, v50
	v_add_f32_e32 v68, v68, v69
	v_add_f32_e32 v48, v48, v49
	v_add_f32_e32 v48, v68, v48
	v_mov_b32_e32 v49, v48
	s_nop 1
	v_permlane16_swap_b32_e32 v49, v48
	v_cvt_pk_bf16_f32 v50, v52, v53
	v_cvt_pk_bf16_f32 v51, v54, v55
	v_cvt_pk_bf16_f32 v52, v60, v61
	v_cvt_pk_bf16_f32 v53, v62, v63
	s_waitcnt lgkmcnt(0)
	v_add_f32_e32 v48, v48, v49
	ds_bpermute_b32 v49, v151, v48
	v_lshl_add_u64 v[54:55], v[66:67], 0, s[26:27]
	global_store_dwordx4 v[54:55], v[50:53], off sc1
	s_nop 1
	s_and_saveexec_b64 s[34:35], s[2:3]
	s_cbranch_execz .LBB0_310
	v_lshlrev_b64 v[50:51], 6, v[64:65]
	v_lshl_add_u64 v[50:51], s[30:31], 0, v[50:51]
	s_waitcnt lgkmcnt(0)
	v_add_f32_e32 v48, v48, v49
	global_store_dword v[50:51], v48, off sc1
; __device__ __forceinline__ void store16_wt(void* p, wt_u32x4 v) { asm volatile("global_store_dwordx4 %0, %1, off sc1\n\ts_nop 1" :: "v"(p), "v"(v) : "memory"); }
; __device__ __forceinline__ float lane_get(float v, int src_lane) { return __builtin_bit_cast(float, __builtin_amdgcn_ds_bpermute(src_lane << 2, __builtin_bit_cast(int, v))); }
; __device__ __forceinline__ unsigned cvt_pk_bf16(float lo, float hi) { unsigned r; asm volatile("v_cvt_pk_bf16_f32 %0, %1, %2" : "=v"(r) : "v"(lo), "v"(hi)); return r; }
;     __device__ __forceinline__ void operator()(const f32x4 (&acc)[2][2][4][2], const Unit& u, int wr, int wc, int fr, int fq, int ui) const {
;     ...
;         const int row0 = u.pm * BM + wr * 64 + fr, col0 = u.pn * BM + wc * 32 + 8 * fq, lane = fq * 16 + fr;
; #pragma unroll
;         for (int ai = 0; ai < 2; ++ai)
; #pragma unroll
;             for (int m = 0; m < 4; ++m) { const int row = row0 + ai * HALF + m * 16; bf16_t* rowb = XB + (size_t)row * ldc + col0; float ss = 0.f;
; #pragma unroll
;                 for (int bj = 0; bj < 2; ++bj) { const f32x4 x0 = acc[ai][bj][m][0], x1 = acc[ai][bj][m][1];
;                     ss += ((x0[0] * x0[0] + x0[1] * x0[1]) + (x0[2] * x0[2] + x0[3] * x0[3])) + ((x1[0] * x1[0] + x1[1] * x1[1]) + (x1[2] * x1[2] + x1[3] * x1[3]));
;                     u32x4 w; w.x = cvt_pk_bf16(x0[0], x0[1]); w.y = cvt_pk_bf16(x0[2], x0[3]); w.z = cvt_pk_bf16(x1[0], x1[1]); w.w = cvt_pk_bf16(x1[2], x1[3]); store16_wt(rowb + bj * HALF, w); }
;                 ss += lane_get(ss, lane ^ 16); ss += lane_get(ss, lane ^ 32);
;                 if (fq == 0) __hip_atomic_store((unsigned*)stats + (size_t)row * 16 + u.pn * 4 + wc, __float_as_uint(ss), __ATOMIC_RELAXED, __HIP_MEMORY_SCOPE_AGENT); }
.LBB0_310:
	s_or_b64 exec, exec, s[34:35]
	v_add_u32_e32 v48, 0x90, v146
	s_waitcnt lgkmcnt(0)
	v_ashrrev_i32_e32 v49, 31, v48
	v_mul_f32_e32 v52, v25, v25
	v_lshlrev_b64 v[50:51], 11, v[48:49]
	v_fmac_f32_e32 v52, v24, v24
	v_mul_f32_e32 v53, v27, v27
	v_cvt_pk_bf16_f32 v24, v24, v25
	v_cvt_pk_bf16_f32 v25, v26, v27
	v_lshl_add_u64 v[50:51], v[144:145], 0, v[50:51]
	v_fmac_f32_e32 v53, v26, v26
	v_cvt_pk_bf16_f32 v26, v32, v33
	v_cvt_pk_bf16_f32 v27, v34, v35
	v_add_f32_e32 v52, v52, v53
	global_store_dwordx4 v[50:51], v[24:27], off sc1
	s_nop 1
	v_mul_f32_e32 v24, v29, v29
	v_mul_f32_e32 v25, v31, v31
	v_fmac_f32_e32 v24, v28, v28
	v_fmac_f32_e32 v25, v30, v30
	v_mul_f32_e32 v53, v33, v33
	v_mul_f32_e32 v54, v35, v35
	v_add_f32_e32 v24, v24, v25
	v_mul_f32_e32 v25, v37, v37
	v_mul_f32_e32 v26, v39, v39
	v_fmac_f32_e32 v53, v32, v32
	v_fmac_f32_e32 v54, v34, v34
	v_fmac_f32_e32 v25, v36, v36
	v_fmac_f32_e32 v26, v38, v38
	v_add_f32_e32 v53, v53, v54
	v_add_f32_e32 v25, v25, v26
	v_add_f32_e32 v52, v52, v53
	v_add_f32_e32 v24, v24, v25
	v_add_f32_e32 v24, v52, v24
	v_mov_b32_e32 v25, v24
	s_nop 1
	v_permlane16_swap_b32_e32 v25, v24
	v_cvt_pk_bf16_f32 v26, v28, v29
	v_cvt_pk_bf16_f32 v27, v30, v31
	v_cvt_pk_bf16_f32 v28, v36, v37
	v_cvt_pk_bf16_f32 v29, v38, v39
	s_waitcnt lgkmcnt(0)
	v_add_f32_e32 v24, v24, v25
	ds_bpermute_b32 v25, v151, v24
	v_lshl_add_u64 v[30:31], v[50:51], 0, s[26:27]
	global_store_dwordx4 v[30:31], v[26:29], off sc1
	s_nop 1
	s_and_saveexec_b64 s[34:35], s[2:3]
	s_cbranch_execz .LBB0_312
	v_lshlrev_b64 v[26:27], 6, v[48:49]
	v_lshl_add_u64 v[26:27], s[30:31], 0, v[26:27]
	s_waitcnt lgkmcnt(0)
	v_add_f32_e32 v24, v24, v25
	global_store_dword v[26:27], v24, off sc1
.LBB0_312:
	s_or_b64 exec, exec, s[34:35]
	v_add_u32_e32 v24, 0xa0, v146
	s_waitcnt lgkmcnt(0)
	v_ashrrev_i32_e32 v25, 31, v24
	v_mul_f32_e32 v28, v1, v1
	v_lshlrev_b64 v[26:27], 11, v[24:25]
	v_fmac_f32_e32 v28, v0, v0
	v_mul_f32_e32 v29, v3, v3
	v_cvt_pk_bf16_f32 v0, v0, v1
	v_cvt_pk_bf16_f32 v1, v2, v3
	v_lshl_add_u64 v[26:27], v[144:145], 0, v[26:27]
	v_fmac_f32_e32 v29, v2, v2
	v_cvt_pk_bf16_f32 v2, v4, v5
	v_cvt_pk_bf16_f32 v3, v6, v7
	v_add_f32_e32 v28, v28, v29
	global_store_dwordx4 v[26:27], v[0:3], off sc1
	s_nop 1
	v_mul_f32_e32 v0, v41, v41
	v_mul_f32_e32 v1, v43, v43
	v_fmac_f32_e32 v0, v40, v40
	v_fmac_f32_e32 v1, v42, v42
	v_mul_f32_e32 v29, v5, v5
	v_mul_f32_e32 v30, v7, v7
	v_add_f32_e32 v0, v0, v1
	v_mul_f32_e32 v1, v45, v45
	v_mul_f32_e32 v2, v47, v47
	v_fmac_f32_e32 v29, v4, v4
	v_fmac_f32_e32 v30, v6, v6
	v_fmac_f32_e32 v1, v44, v44
	v_fmac_f32_e32 v2, v46, v46
	v_add_f32_e32 v29, v29, v30
	v_add_f32_e32 v1, v1, v2
	v_add_f32_e32 v28, v28, v29
	v_add_f32_e32 v0, v0, v1
	v_add_f32_e32 v0, v28, v0
	v_mov_b32_e32 v1, v0
	s_nop 1
	v_permlane16_swap_b32_e32 v1, v0
	v_cvt_pk_bf16_f32 v2, v40, v41
	v_cvt_pk_bf16_f32 v3, v42, v43
	v_cvt_pk_bf16_f32 v4, v44, v45
	v_cvt_pk_bf16_f32 v5, v46, v47
	s_waitcnt lgkmcnt(0)
	v_add_f32_e32 v0, v0, v1
	ds_bpermute_b32 v1, v151, v0
	v_lshl_add_u64 v[6:7], v[26:27], 0, s[26:27]
	global_store_dwordx4 v[6:7], v[2:5], off sc1
	s_nop 1
	s_and_saveexec_b64 s[34:35], s[2:3]
	s_cbranch_execz .LBB0_314
	v_lshlrev_b64 v[2:3], 6, v[24:25]
	v_lshl_add_u64 v[2:3], s[30:31], 0, v[2:3]
	s_waitcnt lgkmcnt(0)
	v_add_f32_e32 v0, v0, v1
	global_store_dword v[2:3], v0, off sc1
.LBB0_314:
	s_or_b64 exec, exec, s[34:35]
	v_add_u32_e32 v0, 0xb0, v146
	s_waitcnt lgkmcnt(0)
	v_ashrrev_i32_e32 v1, 31, v0
	v_lshlrev_b64 v[2:3], 11, v[0:1]
	v_lshl_add_u64 v[24:25], v[144:145], 0, v[2:3]
	v_mul_f32_e32 v2, v9, v9
	v_mul_f32_e32 v3, v11, v11
	v_fmac_f32_e32 v2, v8, v8
	v_fmac_f32_e32 v3, v10, v10
	v_add_f32_e32 v2, v2, v3
	v_mul_f32_e32 v3, v17, v17
	v_mul_f32_e32 v4, v19, v19
	v_fmac_f32_e32 v3, v16, v16
	v_fmac_f32_e32 v4, v18, v18
	v_add_f32_e32 v3, v3, v4
	v_add_f32_e32 v6, v2, v3
	v_cvt_pk_bf16_f32 v2, v8, v9
	v_cvt_pk_bf16_f32 v3, v10, v11
	v_cvt_pk_bf16_f32 v4, v16, v17
	v_cvt_pk_bf16_f32 v5, v18, v19
	v_lshl_add_u64 v[8:9], v[24:25], 0, s[26:27]
	global_store_dwordx4 v[24:25], v[2:5], off sc1
	s_nop 1
	v_mul_f32_e32 v2, v13, v13
	v_mul_f32_e32 v3, v15, v15
	v_fmac_f32_e32 v2, v12, v12
	v_fmac_f32_e32 v3, v14, v14
	v_add_f32_e32 v2, v2, v3
	v_mul_f32_e32 v3, v21, v21
	v_mul_f32_e32 v4, v23, v23
	v_fmac_f32_e32 v3, v20, v20
	v_fmac_f32_e32 v4, v22, v22
	v_add_f32_e32 v3, v3, v4
	v_add_f32_e32 v2, v2, v3
	v_add_f32_e32 v2, v6, v2
	v_mov_b32_e32 v3, v2
	s_nop 1
	v_permlane16_swap_b32_e32 v3, v2
	v_cvt_pk_bf16_f32 v4, v12, v13
	v_cvt_pk_bf16_f32 v5, v14, v15
	v_cvt_pk_bf16_f32 v6, v20, v21
	v_cvt_pk_bf16_f32 v7, v22, v23
	s_waitcnt lgkmcnt(0)
	v_add_f32_e32 v2, v2, v3
	ds_bpermute_b32 v3, v151, v2
	global_store_dwordx4 v[8:9], v[4:7], off sc1
	s_nop 1
	s_and_saveexec_b64 s[34:35], s[2:3]
	s_cbranch_execz .LBB0_316
	v_lshlrev_b64 v[0:1], 6, v[0:1]
	v_lshl_add_u64 v[0:1], s[30:31], 0, v[0:1]
	s_waitcnt lgkmcnt(0)
	v_add_f32_e32 v2, v2, v3
	global_store_dword v[0:1], v2, off sc1

; __device__ __forceinline__ void store16_wt(void* p, wt_u32x4 v) { asm volatile("global_store_dwordx4 %0, %1, off sc1\n\ts_nop 1" :: "v"(p), "v"(v) : "memory"); }
; __device__ __forceinline__ float lane_get(float v, int src_lane) { return __builtin_bit_cast(float, __builtin_amdgcn_ds_bpermute(src_lane << 2, __builtin_bit_cast(int, v))); }
; __device__ __forceinline__ unsigned cvt_pk_bf16(float lo, float hi) { unsigned r; asm volatile("v_cvt_pk_bf16_f32 %0, %1, %2" : "=v"(r) : "v"(lo), "v"(hi)); return r; }
;     __device__ __forceinline__ void operator()(const f32x4 (&acc)[2][2][4][2], const Unit& u, int wr, int wc, int fr, int fq, int ui) const {
;     ...
;         const int row0 = u.pm * BM + wr * 64 + fr, col0 = u.pn * BM + wc * 32 + 8 * fq, lane = fq * 16 + fr;
; #pragma unroll
;         for (int ai = 0; ai < 2; ++ai)
; #pragma unroll
;             for (int m = 0; m < 4; ++m) { const int row = row0 + ai * HALF + m * 16; bf16_t* rowb = XB + (size_t)row * ldc + col0; float ss = 0.f;
; #pragma unroll
;                 for (int bj = 0; bj < 2; ++bj) { const f32x4 x0 = acc[ai][bj][m][0], x1 = acc[ai][bj][m][1];
;                     ss += ((x0[0] * x0[0] + x0[1] * x0[1]) + (x0[2] * x0[2] + x0[3] * x0[3])) + ((x1[0] * x1[0] + x1[1] * x1[1]) + (x1[2] * x1[2] + x1[3] * x1[3]));
;                     u32x4 w; w.x = cvt_pk_bf16(x0[0], x0[1]); w.y = cvt_pk_bf16(x0[2], x0[3]); w.z = cvt_pk_bf16(x1[0], x1[1]); w.w = cvt_pk_bf16(x1[2], x1[3]); store16_wt(rowb + bj * HALF, w); }
;                 ss += lane_get(ss, lane ^ 16); ss += lane_get(ss, lane ^ 32);
;                 if (fq == 0) __hip_atomic_store((unsigned*)stats + (size_t)row * 16 + u.pn * 4 + wc, __float_as_uint(ss), __ATOMIC_RELAXED, __HIP_MEMORY_SCOPE_AGENT); }
.LBB0_675:
	v_lshl_add_u32 v146, s72, 8, v148
	v_lshl_or_b32 v144, s36, 8, v152
	v_ashrrev_i32_e32 v145, 31, v144
	v_ashrrev_i32_e32 v147, 31, v146
	v_mul_f32_e32 v156, v113, v113
	v_lshl_add_u64 v[144:145], v[144:145], 1, s[10:11]
	v_lshlrev_b64 v[154:155], 11, v[146:147]
	v_fmac_f32_e32 v156, v112, v112
	v_mul_f32_e32 v157, v115, v115
	v_cvt_pk_bf16_f32 v112, v112, v113
	v_cvt_pk_bf16_f32 v113, v114, v115
	v_lshl_add_u64 v[154:155], v[144:145], 0, v[154:155]
	v_fmac_f32_e32 v157, v114, v114
	v_cvt_pk_bf16_f32 v114, v120, v121
	v_cvt_pk_bf16_f32 v115, v122, v123
	v_add_f32_e32 v156, v156, v157
	global_store_dwordx4 v[154:155], v[112:115], off sc1
	s_nop 1
	v_mul_f32_e32 v112, v117, v117
	v_mul_f32_e32 v113, v119, v119
	v_fmac_f32_e32 v112, v116, v116
	v_fmac_f32_e32 v113, v118, v118
	v_mul_f32_e32 v157, v121, v121
	v_mul_f32_e32 v158, v123, v123
	v_add_f32_e32 v112, v112, v113
	v_mul_f32_e32 v113, v125, v125
	v_mul_f32_e32 v114, v127, v127
	v_fmac_f32_e32 v157, v120, v120
	v_fmac_f32_e32 v158, v122, v122
	v_fmac_f32_e32 v113, v124, v124
	v_fmac_f32_e32 v114, v126, v126
	v_add_f32_e32 v157, v157, v158
	v_add_f32_e32 v113, v113, v114
	v_add_f32_e32 v156, v156, v157
	v_add_f32_e32 v112, v112, v113
	v_add_f32_e32 v112, v156, v112
	v_mov_b32_e32 v113, v112
	s_nop 1
	v_permlane16_swap_b32_e32 v113, v112
	s_lshl_b32 s6, s36, 2
	s_ashr_i32 s7, s6, 31
	s_lshl_b64 s[6:7], s[6:7], 2
	v_cvt_pk_bf16_f32 v114, v116, v117
	s_waitcnt lgkmcnt(0)
	v_add_f32_e32 v112, v112, v113
	ds_bpermute_b32 v113, v151, v112
	v_cvt_pk_bf16_f32 v115, v118, v119
	v_cvt_pk_bf16_f32 v116, v124, v125
	v_cvt_pk_bf16_f32 v117, v126, v127
	v_lshl_add_u64 v[118:119], v[154:155], 0, s[26:27]
	global_store_dwordx4 v[118:119], v[114:117], off sc1
	s_nop 1
	s_add_u32 s6, s66, s6
	s_addc_u32 s7, s67, s7
	s_and_saveexec_b64 s[36:37], s[2:3]
	s_cbranch_execz .LBB0_677
	v_lshlrev_b64 v[114:115], 6, v[146:147]
	v_lshl_add_u64 v[114:115], s[6:7], 0, v[114:115]
	s_waitcnt lgkmcnt(0)
	v_add_f32_e32 v112, v112, v113
	global_store_dword v[114:115], v112, off sc1
.LBB0_677:
	s_or_b64 exec, exec, s[36:37]
	v_or_b32_e32 v112, 16, v146
	s_waitcnt lgkmcnt(0)
	v_ashrrev_i32_e32 v113, 31, v112
	v_mul_f32_e32 v116, v97, v97
	v_lshlrev_b64 v[114:115], 11, v[112:113]
	v_fmac_f32_e32 v116, v96, v96
	v_mul_f32_e32 v117, v99, v99
	v_cvt_pk_bf16_f32 v96, v96, v97
	v_cvt_pk_bf16_f32 v97, v98, v99
	v_lshl_add_u64 v[114:115], v[144:145], 0, v[114:115]
	v_fmac_f32_e32 v117, v98, v98
	v_cvt_pk_bf16_f32 v98, v104, v105
	v_cvt_pk_bf16_f32 v99, v106, v107
	v_add_f32_e32 v116, v116, v117
	global_store_dwordx4 v[114:115], v[96:99], off sc1
	s_nop 1
	v_mul_f32_e32 v96, v101, v101
	v_mul_f32_e32 v97, v103, v103
	v_fmac_f32_e32 v96, v100, v100
	v_fmac_f32_e32 v97, v102, v102
	v_mul_f32_e32 v117, v105, v105
	v_mul_f32_e32 v118, v107, v107
	v_add_f32_e32 v96, v96, v97
	v_mul_f32_e32 v97, v109, v109
	v_mul_f32_e32 v98, v111, v111
	v_fmac_f32_e32 v117, v104, v104
	v_fmac_f32_e32 v118, v106, v106
	v_fmac_f32_e32 v97, v108, v108
	v_fmac_f32_e32 v98, v110, v110
	v_add_f32_e32 v117, v117, v118
	v_add_f32_e32 v97, v97, v98
	v_add_f32_e32 v116, v116, v117
	v_add_f32_e32 v96, v96, v97
	v_add_f32_e32 v96, v116, v96
	v_mov_b32_e32 v97, v96
	s_nop 1
	v_permlane16_swap_b32_e32 v97, v96
	v_cvt_pk_bf16_f32 v98, v100, v101
	v_cvt_pk_bf16_f32 v99, v102, v103
	v_cvt_pk_bf16_f32 v100, v108, v109
	v_cvt_pk_bf16_f32 v101, v110, v111
	s_waitcnt lgkmcnt(0)
	v_add_f32_e32 v96, v96, v97
	ds_bpermute_b32 v97, v151, v96
	v_lshl_add_u64 v[102:103], v[114:115], 0, s[26:27]
	global_store_dwordx4 v[102:103], v[98:101], off sc1
	s_nop 1
	s_and_saveexec_b64 s[36:37], s[2:3]
	s_cbranch_execz .LBB0_679
	v_lshlrev_b64 v[98:99], 6, v[112:113]
	v_lshl_add_u64 v[98:99], s[6:7], 0, v[98:99]
	s_waitcnt lgkmcnt(0)
	v_add_f32_e32 v96, v96, v97
	global_store_dword v[98:99], v96, off sc1
.LBB0_679:
	s_or_b64 exec, exec, s[36:37]
	v_or_b32_e32 v96, 32, v146
	s_waitcnt lgkmcnt(0)
	v_ashrrev_i32_e32 v97, 31, v96
	v_mul_f32_e32 v100, v81, v81
	v_lshlrev_b64 v[98:99], 11, v[96:97]
	v_fmac_f32_e32 v100, v80, v80
	v_mul_f32_e32 v101, v83, v83
	v_cvt_pk_bf16_f32 v80, v80, v81
	v_cvt_pk_bf16_f32 v81, v82, v83
	v_lshl_add_u64 v[98:99], v[144:145], 0, v[98:99]
	v_fmac_f32_e32 v101, v82, v82
	v_cvt_pk_bf16_f32 v82, v88, v89
	v_cvt_pk_bf16_f32 v83, v90, v91
	v_add_f32_e32 v100, v100, v101
	global_store_dwordx4 v[98:99], v[80:83], off sc1
	s_nop 1
	v_mul_f32_e32 v80, v85, v85
	v_mul_f32_e32 v81, v87, v87
	v_fmac_f32_e32 v80, v84, v84
	v_fmac_f32_e32 v81, v86, v86
	v_mul_f32_e32 v101, v89, v89
	v_mul_f32_e32 v102, v91, v91
	v_add_f32_e32 v80, v80, v81
	v_mul_f32_e32 v81, v93, v93
	v_mul_f32_e32 v82, v95, v95
	v_fmac_f32_e32 v101, v88, v88
	v_fmac_f32_e32 v102, v90, v90
	v_fmac_f32_e32 v81, v92, v92
	v_fmac_f32_e32 v82, v94, v94
	v_add_f32_e32 v101, v101, v102
	v_add_f32_e32 v81, v81, v82
	v_add_f32_e32 v100, v100, v101
	v_add_f32_e32 v80, v80, v81
	v_add_f32_e32 v80, v100, v80
	v_mov_b32_e32 v81, v80
	s_nop 1
	v_permlane16_swap_b32_e32 v81, v80
	v_cvt_pk_bf16_f32 v82, v84, v85
	v_cvt_pk_bf16_f32 v83, v86, v87
	v_cvt_pk_bf16_f32 v84, v92, v93
	v_cvt_pk_bf16_f32 v85, v94, v95
	s_waitcnt lgkmcnt(0)
	v_add_f32_e32 v80, v80, v81
	ds_bpermute_b32 v81, v151, v80
	v_lshl_add_u64 v[86:87], v[98:99], 0, s[26:27]
	global_store_dwordx4 v[86:87], v[82:85], off sc1
	s_nop 1
	s_and_saveexec_b64 s[36:37], s[2:3]
	s_cbranch_execz .LBB0_681
	v_lshlrev_b64 v[82:83], 6, v[96:97]
	v_lshl_add_u64 v[82:83], s[6:7], 0, v[82:83]
	s_waitcnt lgkmcnt(0)
	v_add_f32_e32 v80, v80, v81
	global_store_dword v[82:83], v80, off sc1
; __device__ __forceinline__ void store16_wt(void* p, wt_u32x4 v) { asm volatile("global_store_dwordx4 %0, %1, off sc1\n\ts_nop 1" :: "v"(p), "v"(v) : "memory"); }
; __device__ __forceinline__ float lane_get(float v, int src_lane) { return __builtin_bit_cast(float, __builtin_amdgcn_ds_bpermute(src_lane << 2, __builtin_bit_cast(int, v))); }
; __device__ __forceinline__ unsigned cvt_pk_bf16(float lo, float hi) { unsigned r; asm volatile("v_cvt_pk_bf16_f32 %0, %1, %2" : "=v"(r) : "v"(lo), "v"(hi)); return r; }
;     __device__ __forceinline__ void operator()(const f32x4 (&acc)[2][2][4][2], const Unit& u, int wr, int wc, int fr, int fq, int ui) const {
;     ...
;         const int row0 = u.pm * BM + wr * 64 + fr, col0 = u.pn * BM + wc * 32 + 8 * fq, lane = fq * 16 + fr;
; #pragma unroll
;         for (int ai = 0; ai < 2; ++ai)
; #pragma unroll
;             for (int m = 0; m < 4; ++m) { const int row = row0 + ai * HALF + m * 16; bf16_t* rowb = XB + (size_t)row * ldc + col0; float ss = 0.f;
; #pragma unroll
;                 for (int bj = 0; bj < 2; ++bj) { const f32x4 x0 = acc[ai][bj][m][0], x1 = acc[ai][bj][m][1];
;                     ss += ((x0[0] * x0[0] + x0[1] * x0[1]) + (x0[2] * x0[2] + x0[3] * x0[3])) + ((x1[0] * x1[0] + x1[1] * x1[1]) + (x1[2] * x1[2] + x1[3] * x1[3]));
;                     u32x4 w; w.x = cvt_pk_bf16(x0[0], x0[1]); w.y = cvt_pk_bf16(x0[2], x0[3]); w.z = cvt_pk_bf16(x1[0], x1[1]); w.w = cvt_pk_bf16(x1[2], x1[3]); store16_wt(rowb + bj * HALF, w); }
;                 ss += lane_get(ss, lane ^ 16); ss += lane_get(ss, lane ^ 32);
;                 if (fq == 0) __hip_atomic_store((unsigned*)stats + (size_t)row * 16 + u.pn * 4 + wc, __float_as_uint(ss), __ATOMIC_RELAXED, __HIP_MEMORY_SCOPE_AGENT); }
.LBB0_681:
	s_or_b64 exec, exec, s[36:37]
	v_or_b32_e32 v80, 48, v146
	s_waitcnt lgkmcnt(0)
	v_ashrrev_i32_e32 v81, 31, v80
	v_mul_f32_e32 v84, v65, v65
	v_lshlrev_b64 v[82:83], 11, v[80:81]
	v_fmac_f32_e32 v84, v64, v64
	v_mul_f32_e32 v85, v67, v67
	v_cvt_pk_bf16_f32 v64, v64, v65
	v_cvt_pk_bf16_f32 v65, v66, v67
	v_lshl_add_u64 v[82:83], v[144:145], 0, v[82:83]
	v_fmac_f32_e32 v85, v66, v66
	v_cvt_pk_bf16_f32 v66, v72, v73
	v_cvt_pk_bf16_f32 v67, v74, v75
	v_add_f32_e32 v84, v84, v85
	global_store_dwordx4 v[82:83], v[64:67], off sc1
	s_nop 1
	v_mul_f32_e32 v64, v69, v69
	v_mul_f32_e32 v65, v71, v71
	v_fmac_f32_e32 v64, v68, v68
	v_fmac_f32_e32 v65, v70, v70
	v_mul_f32_e32 v85, v73, v73
	v_mul_f32_e32 v86, v75, v75
	v_add_f32_e32 v64, v64, v65
	v_mul_f32_e32 v65, v77, v77
	v_mul_f32_e32 v66, v79, v79
	v_fmac_f32_e32 v85, v72, v72
	v_fmac_f32_e32 v86, v74, v74
	v_fmac_f32_e32 v65, v76, v76
	v_fmac_f32_e32 v66, v78, v78
	v_add_f32_e32 v85, v85, v86
	v_add_f32_e32 v65, v65, v66
	v_add_f32_e32 v84, v84, v85
	v_add_f32_e32 v64, v64, v65
	v_add_f32_e32 v64, v84, v64
	v_mov_b32_e32 v65, v64
	s_nop 1
	v_permlane16_swap_b32_e32 v65, v64
	v_cvt_pk_bf16_f32 v66, v68, v69
	v_cvt_pk_bf16_f32 v67, v70, v71
	v_cvt_pk_bf16_f32 v68, v76, v77
	v_cvt_pk_bf16_f32 v69, v78, v79
	s_waitcnt lgkmcnt(0)
	v_add_f32_e32 v64, v64, v65
	ds_bpermute_b32 v65, v151, v64
	v_lshl_add_u64 v[70:71], v[82:83], 0, s[26:27]
	global_store_dwordx4 v[70:71], v[66:69], off sc1
	s_nop 1
	s_and_saveexec_b64 s[36:37], s[2:3]
	s_cbranch_execz .LBB0_683
	v_lshlrev_b64 v[66:67], 6, v[80:81]
	v_lshl_add_u64 v[66:67], s[6:7], 0, v[66:67]
	s_waitcnt lgkmcnt(0)
	v_add_f32_e32 v64, v64, v65
	global_store_dword v[66:67], v64, off sc1
.LBB0_683:
	s_or_b64 exec, exec, s[36:37]
	v_add_u32_e32 v64, 0x80, v146
	s_waitcnt lgkmcnt(0)
	v_ashrrev_i32_e32 v65, 31, v64
	v_mul_f32_e32 v68, v49, v49
	v_lshlrev_b64 v[66:67], 11, v[64:65]
	v_fmac_f32_e32 v68, v48, v48
	v_mul_f32_e32 v69, v51, v51
	v_cvt_pk_bf16_f32 v48, v48, v49
	v_cvt_pk_bf16_f32 v49, v50, v51
	v_lshl_add_u64 v[66:67], v[144:145], 0, v[66:67]
	v_fmac_f32_e32 v69, v50, v50
	v_cvt_pk_bf16_f32 v50, v56, v57
	v_cvt_pk_bf16_f32 v51, v58, v59
	v_add_f32_e32 v68, v68, v69
	global_store_dwordx4 v[66:67], v[48:51], off sc1
	s_nop 1
	v_mul_f32_e32 v48, v53, v53
	v_mul_f32_e32 v49, v55, v55
	v_fmac_f32_e32 v48, v52, v52
	v_fmac_f32_e32 v49, v54, v54
	v_mul_f32_e32 v69, v57, v57
	v_mul_f32_e32 v70, v59, v59
	v_add_f32_e32 v48, v48, v49
	v_mul_f32_e32 v49, v61, v61
	v_mul_f32_e32 v50, v63, v63
	v_fmac_f32_e32 v69, v56, v56
	v_fmac_f32_e32 v70, v58, v58
	v_fmac_f32_e32 v49, v60, v60
	v_fmac_f32_e32 v50, v62, v62
	v_add_f32_e32 v69, v69, v70
	v_add_f32_e32 v49, v49, v50
	v_add_f32_e32 v68, v68, v69
	v_add_f32_e32 v48, v48, v49
	v_add_f32_e32 v48, v68, v48
	v_mov_b32_e32 v49, v48
	s_nop 1
	v_permlane16_swap_b32_e32 v49, v48
	v_cvt_pk_bf16_f32 v50, v52, v53
	v_cvt_pk_bf16_f32 v51, v54, v55
	v_cvt_pk_bf16_f32 v52, v60, v61
	v_cvt_pk_bf16_f32 v53, v62, v63
	s_waitcnt lgkmcnt(0)
	v_add_f32_e32 v48, v48, v49
	ds_bpermute_b32 v49, v151, v48
	v_lshl_add_u64 v[54:55], v[66:67], 0, s[26:27]
	global_store_dwordx4 v[54:55], v[50:53], off sc1
	s_nop 1
	s_and_saveexec_b64 s[36:37], s[2:3]
	s_cbranch_execz .LBB0_685
	v_lshlrev_b64 v[50:51], 6, v[64:65]
	v_lshl_add_u64 v[50:51], s[6:7], 0, v[50:51]
	s_waitcnt lgkmcnt(0)
	v_add_f32_e32 v48, v48, v49
	global_store_dword v[50:51], v48, off sc1
; __device__ __forceinline__ void store16_wt(void* p, wt_u32x4 v) { asm volatile("global_store_dwordx4 %0, %1, off sc1\n\ts_nop 1" :: "v"(p), "v"(v) : "memory"); }
; __device__ __forceinline__ float lane_get(float v, int src_lane) { return __builtin_bit_cast(float, __builtin_amdgcn_ds_bpermute(src_lane << 2, __builtin_bit_cast(int, v))); }
; __device__ __forceinline__ unsigned cvt_pk_bf16(float lo, float hi) { unsigned r; asm volatile("v_cvt_pk_bf16_f32 %0, %1, %2" : "=v"(r) : "v"(lo), "v"(hi)); return r; }
;     __device__ __forceinline__ void operator()(const f32x4 (&acc)[2][2][4][2], const Unit& u, int wr, int wc, int fr, int fq, int ui) const {
;     ...
;         const int row0 = u.pm * BM + wr * 64 + fr, col0 = u.pn * BM + wc * 32 + 8 * fq, lane = fq * 16 + fr;
; #pragma unroll
;         for (int ai = 0; ai < 2; ++ai)
; #pragma unroll
;             for (int m = 0; m < 4; ++m) { const int row = row0 + ai * HALF + m * 16; bf16_t* rowb = XB + (size_t)row * ldc + col0; float ss = 0.f;
; #pragma unroll
;                 for (int bj = 0; bj < 2; ++bj) { const f32x4 x0 = acc[ai][bj][m][0], x1 = acc[ai][bj][m][1];
;                     ss += ((x0[0] * x0[0] + x0[1] * x0[1]) + (x0[2] * x0[2] + x0[3] * x0[3])) + ((x1[0] * x1[0] + x1[1] * x1[1]) + (x1[2] * x1[2] + x1[3] * x1[3]));
;                     u32x4 w; w.x = cvt_pk_bf16(x0[0], x0[1]); w.y = cvt_pk_bf16(x0[2], x0[3]); w.z = cvt_pk_bf16(x1[0], x1[1]); w.w = cvt_pk_bf16(x1[2], x1[3]); store16_wt(rowb + bj * HALF, w); }
;                 ss += lane_get(ss, lane ^ 16); ss += lane_get(ss, lane ^ 32);
;                 if (fq == 0) __hip_atomic_store((unsigned*)stats + (size_t)row * 16 + u.pn * 4 + wc, __float_as_uint(ss), __ATOMIC_RELAXED, __HIP_MEMORY_SCOPE_AGENT); }
.LBB0_685:
	s_or_b64 exec, exec, s[36:37]
	v_add_u32_e32 v48, 0x90, v146
	s_waitcnt lgkmcnt(0)
	v_ashrrev_i32_e32 v49, 31, v48
	v_mul_f32_e32 v52, v25, v25
	v_lshlrev_b64 v[50:51], 11, v[48:49]
	v_fmac_f32_e32 v52, v24, v24
	v_mul_f32_e32 v53, v27, v27
	v_cvt_pk_bf16_f32 v24, v24, v25
	v_cvt_pk_bf16_f32 v25, v26, v27
	v_lshl_add_u64 v[50:51], v[144:145], 0, v[50:51]
	v_fmac_f32_e32 v53, v26, v26
	v_cvt_pk_bf16_f32 v26, v32, v33
	v_cvt_pk_bf16_f32 v27, v34, v35
	v_add_f32_e32 v52, v52, v53
	global_store_dwordx4 v[50:51], v[24:27], off sc1
	s_nop 1
	v_mul_f32_e32 v24, v29, v29
	v_mul_f32_e32 v25, v31, v31
	v_fmac_f32_e32 v24, v28, v28
	v_fmac_f32_e32 v25, v30, v30
	v_mul_f32_e32 v53, v33, v33
	v_mul_f32_e32 v54, v35, v35
	v_add_f32_e32 v24, v24, v25
	v_mul_f32_e32 v25, v37, v37
	v_mul_f32_e32 v26, v39, v39
	v_fmac_f32_e32 v53, v32, v32
	v_fmac_f32_e32 v54, v34, v34
	v_fmac_f32_e32 v25, v36, v36
	v_fmac_f32_e32 v26, v38, v38
	v_add_f32_e32 v53, v53, v54
	v_add_f32_e32 v25, v25, v26
	v_add_f32_e32 v52, v52, v53
	v_add_f32_e32 v24, v24, v25
	v_add_f32_e32 v24, v52, v24
	v_mov_b32_e32 v25, v24
	s_nop 1
	v_permlane16_swap_b32_e32 v25, v24
	v_cvt_pk_bf16_f32 v26, v28, v29
	v_cvt_pk_bf16_f32 v27, v30, v31
	v_cvt_pk_bf16_f32 v28, v36, v37
	v_cvt_pk_bf16_f32 v29, v38, v39
	s_waitcnt lgkmcnt(0)
	v_add_f32_e32 v24, v24, v25
	ds_bpermute_b32 v25, v151, v24
	v_lshl_add_u64 v[30:31], v[50:51], 0, s[26:27]
	global_store_dwordx4 v[30:31], v[26:29], off sc1
	s_nop 1
	s_and_saveexec_b64 s[36:37], s[2:3]
	s_cbranch_execz .LBB0_687
	v_lshlrev_b64 v[26:27], 6, v[48:49]
	v_lshl_add_u64 v[26:27], s[6:7], 0, v[26:27]
	s_waitcnt lgkmcnt(0)
	v_add_f32_e32 v24, v24, v25
	global_store_dword v[26:27], v24, off sc1
.LBB0_687:
	s_or_b64 exec, exec, s[36:37]
	v_add_u32_e32 v24, 0xa0, v146
	s_waitcnt lgkmcnt(0)
	v_ashrrev_i32_e32 v25, 31, v24
	v_mul_f32_e32 v28, v1, v1
	v_lshlrev_b64 v[26:27], 11, v[24:25]
	v_fmac_f32_e32 v28, v0, v0
	v_mul_f32_e32 v29, v3, v3
	v_cvt_pk_bf16_f32 v0, v0, v1
	v_cvt_pk_bf16_f32 v1, v2, v3
	v_lshl_add_u64 v[26:27], v[144:145], 0, v[26:27]
	v_fmac_f32_e32 v29, v2, v2
	v_cvt_pk_bf16_f32 v2, v4, v5
	v_cvt_pk_bf16_f32 v3, v6, v7
	v_add_f32_e32 v28, v28, v29
	global_store_dwordx4 v[26:27], v[0:3], off sc1
	s_nop 1
	v_mul_f32_e32 v0, v41, v41
	v_mul_f32_e32 v1, v43, v43
	v_fmac_f32_e32 v0, v40, v40
	v_fmac_f32_e32 v1, v42, v42
	v_mul_f32_e32 v29, v5, v5
	v_mul_f32_e32 v30, v7, v7
	v_add_f32_e32 v0, v0, v1
	v_mul_f32_e32 v1, v45, v45
	v_mul_f32_e32 v2, v47, v47
	v_fmac_f32_e32 v29, v4, v4
	v_fmac_f32_e32 v30, v6, v6
	v_fmac_f32_e32 v1, v44, v44
	v_fmac_f32_e32 v2, v46, v46
	v_add_f32_e32 v29, v29, v30
	v_add_f32_e32 v1, v1, v2
	v_add_f32_e32 v28, v28, v29
	v_add_f32_e32 v0, v0, v1
	v_add_f32_e32 v0, v28, v0
	v_mov_b32_e32 v1, v0
	s_nop 1
	v_permlane16_swap_b32_e32 v1, v0
	v_cvt_pk_bf16_f32 v2, v40, v41
	v_cvt_pk_bf16_f32 v3, v42, v43
	v_cvt_pk_bf16_f32 v4, v44, v45
	v_cvt_pk_bf16_f32 v5, v46, v47
	s_waitcnt lgkmcnt(0)
	v_add_f32_e32 v0, v0, v1
	ds_bpermute_b32 v1, v151, v0
	v_lshl_add_u64 v[6:7], v[26:27], 0, s[26:27]
	global_store_dwordx4 v[6:7], v[2:5], off sc1
	s_nop 1
	s_and_saveexec_b64 s[36:37], s[2:3]
	s_cbranch_execz .LBB0_689
	v_lshlrev_b64 v[2:3], 6, v[24:25]
	v_lshl_add_u64 v[2:3], s[6:7], 0, v[2:3]
	s_waitcnt lgkmcnt(0)
	v_add_f32_e32 v0, v0, v1
	global_store_dword v[2:3], v0, off sc1
.LBB0_689:
	s_or_b64 exec, exec, s[36:37]
	v_add_u32_e32 v0, 0xb0, v146
	s_waitcnt lgkmcnt(0)
	v_ashrrev_i32_e32 v1, 31, v0
	v_lshlrev_b64 v[2:3], 11, v[0:1]
	v_lshl_add_u64 v[24:25], v[144:145], 0, v[2:3]
	v_mul_f32_e32 v2, v9, v9
	v_mul_f32_e32 v3, v11, v11
	v_fmac_f32_e32 v2, v8, v8
	v_fmac_f32_e32 v3, v10, v10
	v_add_f32_e32 v2, v2, v3
	v_mul_f32_e32 v3, v17, v17
	v_mul_f32_e32 v4, v19, v19
	v_fmac_f32_e32 v3, v16, v16
	v_fmac_f32_e32 v4, v18, v18
	v_add_f32_e32 v3, v3, v4
	v_add_f32_e32 v6, v2, v3
	v_cvt_pk_bf16_f32 v2, v8, v9
	v_cvt_pk_bf16_f32 v3, v10, v11
	v_cvt_pk_bf16_f32 v4, v16, v17
	v_cvt_pk_bf16_f32 v5, v18, v19
	v_lshl_add_u64 v[8:9], v[24:25], 0, s[26:27]
	global_store_dwordx4 v[24:25], v[2:5], off sc1
	s_nop 1
	v_mul_f32_e32 v2, v13, v13
	v_mul_f32_e32 v3, v15, v15
	v_fmac_f32_e32 v2, v12, v12
	v_fmac_f32_e32 v3, v14, v14
	v_add_f32_e32 v2, v2, v3
	v_mul_f32_e32 v3, v21, v21
	v_mul_f32_e32 v4, v23, v23
	v_fmac_f32_e32 v3, v20, v20
	v_fmac_f32_e32 v4, v22, v22
	v_add_f32_e32 v3, v3, v4
	v_add_f32_e32 v2, v2, v3
	v_add_f32_e32 v2, v6, v2
	v_mov_b32_e32 v3, v2
	s_nop 1
	v_permlane16_swap_b32_e32 v3, v2
	v_cvt_pk_bf16_f32 v4, v12, v13
	v_cvt_pk_bf16_f32 v5, v14, v15
	v_cvt_pk_bf16_f32 v6, v20, v21
	v_cvt_pk_bf16_f32 v7, v22, v23
	s_waitcnt lgkmcnt(0)
	v_add_f32_e32 v2, v2, v3
	ds_bpermute_b32 v3, v151, v2
	global_store_dwordx4 v[8:9], v[4:7], off sc1
	s_nop 1
	s_and_saveexec_b64 s[36:37], s[2:3]
	s_cbranch_execz .LBB0_691
	v_lshlrev_b64 v[0:1], 6, v[0:1]
	v_lshl_add_u64 v[0:1], s[6:7], 0, v[0:1]
	s_waitcnt lgkmcnt(0)
	v_add_f32_e32 v2, v2, v3
	global_store_dword v[0:1], v2, off sc1

; __device__ __forceinline__ void store16_wt(void* p, wt_u32x4 v) { asm volatile("global_store_dwordx4 %0, %1, off sc1\n\ts_nop 1" :: "v"(p), "v"(v) : "memory"); }
; __device__ __forceinline__ float lane_get(float v, int src_lane) { return __builtin_bit_cast(float, __builtin_amdgcn_ds_bpermute(src_lane << 2, __builtin_bit_cast(int, v))); }
; __device__ __forceinline__ unsigned cvt_pk_bf16(float lo, float hi) { unsigned r; asm volatile("v_cvt_pk_bf16_f32 %0, %1, %2" : "=v"(r) : "v"(lo), "v"(hi)); return r; }
;     __device__ __forceinline__ void operator()(const f32x4 (&acc)[2][2][4][2], const Unit& u, int wr, int wc, int fr, int fq, int ui) const {
;     ...
;         const int row0 = u.pm * BM + wr * 64 + fr, col0 = u.pn * BM + wc * 32 + 8 * fq, lane = fq * 16 + fr;
; #pragma unroll
;         for (int ai = 0; ai < 2; ++ai)
; #pragma unroll
;             for (int m = 0; m < 4; ++m) { const int row = row0 + ai * HALF + m * 16; bf16_t* rowb = XB + (size_t)row * ldc + col0; float ss = 0.f;
; #pragma unroll
;                 for (int bj = 0; bj < 2; ++bj) { const f32x4 x0 = acc[ai][bj][m][0], x1 = acc[ai][bj][m][1];
;                     ss += ((x0[0] * x0[0] + x0[1] * x0[1]) + (x0[2] * x0[2] + x0[3] * x0[3])) + ((x1[0] * x1[0] + x1[1] * x1[1]) + (x1[2] * x1[2] + x1[3] * x1[3]));
;                     u32x4 w; w.x = cvt_pk_bf16(x0[0], x0[1]); w.y = cvt_pk_bf16(x0[2], x0[3]); w.z = cvt_pk_bf16(x1[0], x1[1]); w.w = cvt_pk_bf16(x1[2], x1[3]); store16_wt(rowb + bj * HALF, w); }
;                 ss += lane_get(ss, lane ^ 16); ss += lane_get(ss, lane ^ 32);
;                 if (fq == 0) __hip_atomic_store((unsigned*)stats + (size_t)row * 16 + u.pn * 4 + wc, __float_as_uint(ss), __ATOMIC_RELAXED, __HIP_MEMORY_SCOPE_AGENT); }
.LBB0_889:
	v_lshl_add_u32 v138, s40, 8, v148
	v_lshl_or_b32 v136, s38, 8, v152
	v_ashrrev_i32_e32 v137, 31, v136
	v_ashrrev_i32_e32 v139, 31, v138
	v_mul_f32_e32 v156, v113, v113
	v_lshl_add_u64 v[136:137], v[136:137], 1, s[12:13]
	v_lshlrev_b64 v[154:155], 11, v[138:139]
	v_fmac_f32_e32 v156, v112, v112
	v_mul_f32_e32 v157, v115, v115
	v_cvt_pk_bf16_f32 v112, v112, v113
	v_cvt_pk_bf16_f32 v113, v114, v115
	v_lshl_add_u64 v[154:155], v[136:137], 0, v[154:155]
	v_fmac_f32_e32 v157, v114, v114
	v_cvt_pk_bf16_f32 v114, v120, v121
	v_cvt_pk_bf16_f32 v115, v122, v123
	v_add_f32_e32 v156, v156, v157
	global_store_dwordx4 v[154:155], v[112:115], off sc1
	s_nop 1
	v_mul_f32_e32 v112, v117, v117
	v_mul_f32_e32 v113, v119, v119
	v_fmac_f32_e32 v112, v116, v116
	v_fmac_f32_e32 v113, v118, v118
	v_mul_f32_e32 v157, v121, v121
	v_mul_f32_e32 v158, v123, v123
	v_add_f32_e32 v112, v112, v113
	v_mul_f32_e32 v113, v125, v125
	v_mul_f32_e32 v114, v127, v127
	v_fmac_f32_e32 v157, v120, v120
	v_fmac_f32_e32 v158, v122, v122
	v_fmac_f32_e32 v113, v124, v124
	v_fmac_f32_e32 v114, v126, v126
	v_add_f32_e32 v157, v157, v158
	v_add_f32_e32 v113, v113, v114
	v_add_f32_e32 v156, v156, v157
	v_add_f32_e32 v112, v112, v113
	v_add_f32_e32 v112, v156, v112
	v_mov_b32_e32 v113, v112
	s_nop 1
	v_permlane16_swap_b32_e32 v113, v112
	s_lshl_b32 s38, s38, 2
	s_ashr_i32 s39, s38, 31
	s_lshl_b64 s[38:39], s[38:39], 2
	v_cvt_pk_bf16_f32 v114, v116, v117
	s_waitcnt lgkmcnt(0)
	v_add_f32_e32 v112, v112, v113
	ds_bpermute_b32 v113, v151, v112
	v_cvt_pk_bf16_f32 v115, v118, v119
	v_cvt_pk_bf16_f32 v116, v124, v125
	v_cvt_pk_bf16_f32 v117, v126, v127
	v_lshl_add_u64 v[118:119], v[154:155], 0, s[14:15]
	global_store_dwordx4 v[118:119], v[114:117], off sc1
	s_nop 1
	s_add_u32 s38, s64, s38
	s_addc_u32 s39, s65, s39
	s_and_saveexec_b64 s[40:41], s[2:3]
	s_cbranch_execz .LBB0_891
	v_lshlrev_b64 v[114:115], 6, v[138:139]
	v_lshl_add_u64 v[114:115], s[38:39], 0, v[114:115]
	s_waitcnt lgkmcnt(0)
	v_add_f32_e32 v112, v112, v113
	global_store_dword v[114:115], v112, off sc1
.LBB0_891:
	s_or_b64 exec, exec, s[40:41]
	v_or_b32_e32 v112, 16, v138
	s_waitcnt lgkmcnt(0)
	v_ashrrev_i32_e32 v113, 31, v112
	v_mul_f32_e32 v116, v97, v97
	v_lshlrev_b64 v[114:115], 11, v[112:113]
	v_fmac_f32_e32 v116, v96, v96
	v_mul_f32_e32 v117, v99, v99
	v_cvt_pk_bf16_f32 v96, v96, v97
	v_cvt_pk_bf16_f32 v97, v98, v99
	v_lshl_add_u64 v[114:115], v[136:137], 0, v[114:115]
	v_fmac_f32_e32 v117, v98, v98
	v_cvt_pk_bf16_f32 v98, v104, v105
	v_cvt_pk_bf16_f32 v99, v106, v107
	v_add_f32_e32 v116, v116, v117
	global_store_dwordx4 v[114:115], v[96:99], off sc1
	s_nop 1
	v_mul_f32_e32 v96, v101, v101
	v_mul_f32_e32 v97, v103, v103
	v_fmac_f32_e32 v96, v100, v100
	v_fmac_f32_e32 v97, v102, v102
	v_mul_f32_e32 v117, v105, v105
	v_mul_f32_e32 v118, v107, v107
	v_add_f32_e32 v96, v96, v97
	v_mul_f32_e32 v97, v109, v109
	v_mul_f32_e32 v98, v111, v111
	v_fmac_f32_e32 v117, v104, v104
	v_fmac_f32_e32 v118, v106, v106
	v_fmac_f32_e32 v97, v108, v108
	v_fmac_f32_e32 v98, v110, v110
	v_add_f32_e32 v117, v117, v118
	v_add_f32_e32 v97, v97, v98
	v_add_f32_e32 v116, v116, v117
	v_add_f32_e32 v96, v96, v97
	v_add_f32_e32 v96, v116, v96
	v_mov_b32_e32 v97, v96
	s_nop 1
	v_permlane16_swap_b32_e32 v97, v96
	v_cvt_pk_bf16_f32 v98, v100, v101
	v_cvt_pk_bf16_f32 v99, v102, v103
	v_cvt_pk_bf16_f32 v100, v108, v109
	v_cvt_pk_bf16_f32 v101, v110, v111
	s_waitcnt lgkmcnt(0)
	v_add_f32_e32 v96, v96, v97
	ds_bpermute_b32 v97, v151, v96
	v_lshl_add_u64 v[102:103], v[114:115], 0, s[14:15]
	global_store_dwordx4 v[102:103], v[98:101], off sc1
	s_nop 1
	s_and_saveexec_b64 s[40:41], s[2:3]
	s_cbranch_execz .LBB0_893
	v_lshlrev_b64 v[98:99], 6, v[112:113]
	v_lshl_add_u64 v[98:99], s[38:39], 0, v[98:99]
	s_waitcnt lgkmcnt(0)
	v_add_f32_e32 v96, v96, v97
	global_store_dword v[98:99], v96, off sc1
.LBB0_893:
	s_or_b64 exec, exec, s[40:41]
	v_or_b32_e32 v96, 32, v138
	s_waitcnt lgkmcnt(0)
	v_ashrrev_i32_e32 v97, 31, v96
	v_mul_f32_e32 v100, v81, v81
	v_lshlrev_b64 v[98:99], 11, v[96:97]
	v_fmac_f32_e32 v100, v80, v80
	v_mul_f32_e32 v101, v83, v83
	v_cvt_pk_bf16_f32 v80, v80, v81
	v_cvt_pk_bf16_f32 v81, v82, v83
	v_lshl_add_u64 v[98:99], v[136:137], 0, v[98:99]
	v_fmac_f32_e32 v101, v82, v82
	v_cvt_pk_bf16_f32 v82, v88, v89
	v_cvt_pk_bf16_f32 v83, v90, v91
	v_add_f32_e32 v100, v100, v101
	global_store_dwordx4 v[98:99], v[80:83], off sc1
	s_nop 1
	v_mul_f32_e32 v80, v85, v85
	v_mul_f32_e32 v81, v87, v87
	v_fmac_f32_e32 v80, v84, v84
	v_fmac_f32_e32 v81, v86, v86
	v_mul_f32_e32 v101, v89, v89
	v_mul_f32_e32 v102, v91, v91
	v_add_f32_e32 v80, v80, v81
	v_mul_f32_e32 v81, v93, v93
	v_mul_f32_e32 v82, v95, v95
	v_fmac_f32_e32 v101, v88, v88
	v_fmac_f32_e32 v102, v90, v90
	v_fmac_f32_e32 v81, v92, v92
	v_fmac_f32_e32 v82, v94, v94
	v_add_f32_e32 v101, v101, v102
	v_add_f32_e32 v81, v81, v82
	v_add_f32_e32 v100, v100, v101
	v_add_f32_e32 v80, v80, v81
	v_add_f32_e32 v80, v100, v80
	v_mov_b32_e32 v81, v80
	s_nop 1
	v_permlane16_swap_b32_e32 v81, v80
	v_cvt_pk_bf16_f32 v82, v84, v85
	v_cvt_pk_bf16_f32 v83, v86, v87
	v_cvt_pk_bf16_f32 v84, v92, v93
	v_cvt_pk_bf16_f32 v85, v94, v95
	s_waitcnt lgkmcnt(0)
	v_add_f32_e32 v80, v80, v81
	ds_bpermute_b32 v81, v151, v80
	v_lshl_add_u64 v[86:87], v[98:99], 0, s[14:15]
	global_store_dwordx4 v[86:87], v[82:85], off sc1
	s_nop 1
	s_and_saveexec_b64 s[40:41], s[2:3]
	s_cbranch_execz .LBB0_895
	v_lshlrev_b64 v[82:83], 6, v[96:97]
	v_lshl_add_u64 v[82:83], s[38:39], 0, v[82:83]
	s_waitcnt lgkmcnt(0)
	v_add_f32_e32 v80, v80, v81
	global_store_dword v[82:83], v80, off sc1
; __device__ __forceinline__ void store16_wt(void* p, wt_u32x4 v) { asm volatile("global_store_dwordx4 %0, %1, off sc1\n\ts_nop 1" :: "v"(p), "v"(v) : "memory"); }
; __device__ __forceinline__ float lane_get(float v, int src_lane) { return __builtin_bit_cast(float, __builtin_amdgcn_ds_bpermute(src_lane << 2, __builtin_bit_cast(int, v))); }
; __device__ __forceinline__ unsigned cvt_pk_bf16(float lo, float hi) { unsigned r; asm volatile("v_cvt_pk_bf16_f32 %0, %1, %2" : "=v"(r) : "v"(lo), "v"(hi)); return r; }
;     __device__ __forceinline__ void operator()(const f32x4 (&acc)[2][2][4][2], const Unit& u, int wr, int wc, int fr, int fq, int ui) const {
;     ...
;         const int row0 = u.pm * BM + wr * 64 + fr, col0 = u.pn * BM + wc * 32 + 8 * fq, lane = fq * 16 + fr;
; #pragma unroll
;         for (int ai = 0; ai < 2; ++ai)
; #pragma unroll
;             for (int m = 0; m < 4; ++m) { const int row = row0 + ai * HALF + m * 16; bf16_t* rowb = XB + (size_t)row * ldc + col0; float ss = 0.f;
; #pragma unroll
;                 for (int bj = 0; bj < 2; ++bj) { const f32x4 x0 = acc[ai][bj][m][0], x1 = acc[ai][bj][m][1];
;                     ss += ((x0[0] * x0[0] + x0[1] * x0[1]) + (x0[2] * x0[2] + x0[3] * x0[3])) + ((x1[0] * x1[0] + x1[1] * x1[1]) + (x1[2] * x1[2] + x1[3] * x1[3]));
;                     u32x4 w; w.x = cvt_pk_bf16(x0[0], x0[1]); w.y = cvt_pk_bf16(x0[2], x0[3]); w.z = cvt_pk_bf16(x1[0], x1[1]); w.w = cvt_pk_bf16(x1[2], x1[3]); store16_wt(rowb + bj * HALF, w); }
;                 ss += lane_get(ss, lane ^ 16); ss += lane_get(ss, lane ^ 32);
;                 if (fq == 0) __hip_atomic_store((unsigned*)stats + (size_t)row * 16 + u.pn * 4 + wc, __float_as_uint(ss), __ATOMIC_RELAXED, __HIP_MEMORY_SCOPE_AGENT); }
.LBB0_895:
	s_or_b64 exec, exec, s[40:41]
	v_or_b32_e32 v80, 48, v138
	s_waitcnt lgkmcnt(0)
	v_ashrrev_i32_e32 v81, 31, v80
	v_mul_f32_e32 v84, v65, v65
	v_lshlrev_b64 v[82:83], 11, v[80:81]
	v_fmac_f32_e32 v84, v64, v64
	v_mul_f32_e32 v85, v67, v67
	v_cvt_pk_bf16_f32 v64, v64, v65
	v_cvt_pk_bf16_f32 v65, v66, v67
	v_lshl_add_u64 v[82:83], v[136:137], 0, v[82:83]
	v_fmac_f32_e32 v85, v66, v66
	v_cvt_pk_bf16_f32 v66, v72, v73
	v_cvt_pk_bf16_f32 v67, v74, v75
	v_add_f32_e32 v84, v84, v85
	global_store_dwordx4 v[82:83], v[64:67], off sc1
	s_nop 1
	v_mul_f32_e32 v64, v69, v69
	v_mul_f32_e32 v65, v71, v71
	v_fmac_f32_e32 v64, v68, v68
	v_fmac_f32_e32 v65, v70, v70
	v_mul_f32_e32 v85, v73, v73
	v_mul_f32_e32 v86, v75, v75
	v_add_f32_e32 v64, v64, v65
	v_mul_f32_e32 v65, v77, v77
	v_mul_f32_e32 v66, v79, v79
	v_fmac_f32_e32 v85, v72, v72
	v_fmac_f32_e32 v86, v74, v74
	v_fmac_f32_e32 v65, v76, v76
	v_fmac_f32_e32 v66, v78, v78
	v_add_f32_e32 v85, v85, v86
	v_add_f32_e32 v65, v65, v66
	v_add_f32_e32 v84, v84, v85
	v_add_f32_e32 v64, v64, v65
	v_add_f32_e32 v64, v84, v64
	v_mov_b32_e32 v65, v64
	s_nop 1
	v_permlane16_swap_b32_e32 v65, v64
	v_cvt_pk_bf16_f32 v66, v68, v69
	v_cvt_pk_bf16_f32 v67, v70, v71
	v_cvt_pk_bf16_f32 v68, v76, v77
	v_cvt_pk_bf16_f32 v69, v78, v79
	s_waitcnt lgkmcnt(0)
	v_add_f32_e32 v64, v64, v65
	ds_bpermute_b32 v65, v151, v64
	v_lshl_add_u64 v[70:71], v[82:83], 0, s[14:15]
	global_store_dwordx4 v[70:71], v[66:69], off sc1
	s_nop 1
	s_and_saveexec_b64 s[40:41], s[2:3]
	s_cbranch_execz .LBB0_897
	v_lshlrev_b64 v[66:67], 6, v[80:81]
	v_lshl_add_u64 v[66:67], s[38:39], 0, v[66:67]
	s_waitcnt lgkmcnt(0)
	v_add_f32_e32 v64, v64, v65
	global_store_dword v[66:67], v64, off sc1
.LBB0_897:
	s_or_b64 exec, exec, s[40:41]
	v_add_u32_e32 v64, 0x80, v138
	s_waitcnt lgkmcnt(0)
	v_ashrrev_i32_e32 v65, 31, v64
	v_mul_f32_e32 v68, v49, v49
	v_lshlrev_b64 v[66:67], 11, v[64:65]
	v_fmac_f32_e32 v68, v48, v48
	v_mul_f32_e32 v69, v51, v51
	v_cvt_pk_bf16_f32 v48, v48, v49
	v_cvt_pk_bf16_f32 v49, v50, v51
	v_lshl_add_u64 v[66:67], v[136:137], 0, v[66:67]
	v_fmac_f32_e32 v69, v50, v50
	v_cvt_pk_bf16_f32 v50, v56, v57
	v_cvt_pk_bf16_f32 v51, v58, v59
	v_add_f32_e32 v68, v68, v69
	global_store_dwordx4 v[66:67], v[48:51], off sc1
	s_nop 1
	v_mul_f32_e32 v48, v53, v53
	v_mul_f32_e32 v49, v55, v55
	v_fmac_f32_e32 v48, v52, v52
	v_fmac_f32_e32 v49, v54, v54
	v_mul_f32_e32 v69, v57, v57
	v_mul_f32_e32 v70, v59, v59
	v_add_f32_e32 v48, v48, v49
	v_mul_f32_e32 v49, v61, v61
	v_mul_f32_e32 v50, v63, v63
	v_fmac_f32_e32 v69, v56, v56
	v_fmac_f32_e32 v70, v58, v58
	v_fmac_f32_e32 v49, v60, v60
	v_fmac_f32_e32 v50, v62, v62
	v_add_f32_e32 v69, v69, v70
	v_add_f32_e32 v49, v49, v50
	v_add_f32_e32 v68, v68, v69
	v_add_f32_e32 v48, v48, v49
	v_add_f32_e32 v48, v68, v48
	v_mov_b32_e32 v49, v48
	s_nop 1
	v_permlane16_swap_b32_e32 v49, v48
	v_cvt_pk_bf16_f32 v50, v52, v53
	v_cvt_pk_bf16_f32 v51, v54, v55
	v_cvt_pk_bf16_f32 v52, v60, v61
	v_cvt_pk_bf16_f32 v53, v62, v63
	s_waitcnt lgkmcnt(0)
	v_add_f32_e32 v48, v48, v49
	ds_bpermute_b32 v49, v151, v48
	v_lshl_add_u64 v[54:55], v[66:67], 0, s[14:15]
	global_store_dwordx4 v[54:55], v[50:53], off sc1
	s_nop 1
	s_and_saveexec_b64 s[40:41], s[2:3]
	s_cbranch_execz .LBB0_899
	v_lshlrev_b64 v[50:51], 6, v[64:65]
	v_lshl_add_u64 v[50:51], s[38:39], 0, v[50:51]
	s_waitcnt lgkmcnt(0)
	v_add_f32_e32 v48, v48, v49
	global_store_dword v[50:51], v48, off sc1
; __device__ __forceinline__ void store16_wt(void* p, wt_u32x4 v) { asm volatile("global_store_dwordx4 %0, %1, off sc1\n\ts_nop 1" :: "v"(p), "v"(v) : "memory"); }
; __device__ __forceinline__ float lane_get(float v, int src_lane) { return __builtin_bit_cast(float, __builtin_amdgcn_ds_bpermute(src_lane << 2, __builtin_bit_cast(int, v))); }
; __device__ __forceinline__ unsigned cvt_pk_bf16(float lo, float hi) { unsigned r; asm volatile("v_cvt_pk_bf16_f32 %0, %1, %2" : "=v"(r) : "v"(lo), "v"(hi)); return r; }
;     __device__ __forceinline__ void operator()(const f32x4 (&acc)[2][2][4][2], const Unit& u, int wr, int wc, int fr, int fq, int ui) const {
;     ...
;         const int row0 = u.pm * BM + wr * 64 + fr, col0 = u.pn * BM + wc * 32 + 8 * fq, lane = fq * 16 + fr;
; #pragma unroll
;         for (int ai = 0; ai < 2; ++ai)
; #pragma unroll
;             for (int m = 0; m < 4; ++m) { const int row = row0 + ai * HALF + m * 16; bf16_t* rowb = XB + (size_t)row * ldc + col0; float ss = 0.f;
; #pragma unroll
;                 for (int bj = 0; bj < 2; ++bj) { const f32x4 x0 = acc[ai][bj][m][0], x1 = acc[ai][bj][m][1];
;                     ss += ((x0[0] * x0[0] + x0[1] * x0[1]) + (x0[2] * x0[2] + x0[3] * x0[3])) + ((x1[0] * x1[0] + x1[1] * x1[1]) + (x1[2] * x1[2] + x1[3] * x1[3]));
;                     u32x4 w; w.x = cvt_pk_bf16(x0[0], x0[1]); w.y = cvt_pk_bf16(x0[2], x0[3]); w.z = cvt_pk_bf16(x1[0], x1[1]); w.w = cvt_pk_bf16(x1[2], x1[3]); store16_wt(rowb + bj * HALF, w); }
;                 ss += lane_get(ss, lane ^ 16); ss += lane_get(ss, lane ^ 32);
;                 if (fq == 0) __hip_atomic_store((unsigned*)stats + (size_t)row * 16 + u.pn * 4 + wc, __float_as_uint(ss), __ATOMIC_RELAXED, __HIP_MEMORY_SCOPE_AGENT); }
.LBB0_899:
	s_or_b64 exec, exec, s[40:41]
	v_add_u32_e32 v48, 0x90, v138
	s_waitcnt lgkmcnt(0)
	v_ashrrev_i32_e32 v49, 31, v48
	v_mul_f32_e32 v52, v17, v17
	v_lshlrev_b64 v[50:51], 11, v[48:49]
	v_fmac_f32_e32 v52, v16, v16
	v_mul_f32_e32 v53, v19, v19
	v_cvt_pk_bf16_f32 v16, v16, v17
	v_cvt_pk_bf16_f32 v17, v18, v19
	v_lshl_add_u64 v[50:51], v[136:137], 0, v[50:51]
	v_fmac_f32_e32 v53, v18, v18
	v_cvt_pk_bf16_f32 v18, v24, v25
	v_cvt_pk_bf16_f32 v19, v26, v27
	v_add_f32_e32 v52, v52, v53
	global_store_dwordx4 v[50:51], v[16:19], off sc1
	s_nop 1
	v_mul_f32_e32 v16, v21, v21
	v_mul_f32_e32 v17, v23, v23
	v_fmac_f32_e32 v16, v20, v20
	v_fmac_f32_e32 v17, v22, v22
	v_mul_f32_e32 v53, v25, v25
	v_mul_f32_e32 v54, v27, v27
	v_add_f32_e32 v16, v16, v17
	v_mul_f32_e32 v17, v29, v29
	v_mul_f32_e32 v18, v31, v31
	v_fmac_f32_e32 v53, v24, v24
	v_fmac_f32_e32 v54, v26, v26
	v_fmac_f32_e32 v17, v28, v28
	v_fmac_f32_e32 v18, v30, v30
	v_add_f32_e32 v53, v53, v54
	v_add_f32_e32 v17, v17, v18
	v_add_f32_e32 v52, v52, v53
	v_add_f32_e32 v16, v16, v17
	v_add_f32_e32 v16, v52, v16
	v_mov_b32_e32 v17, v16
	s_nop 1
	v_permlane16_swap_b32_e32 v17, v16
	v_cvt_pk_bf16_f32 v18, v20, v21
	v_cvt_pk_bf16_f32 v19, v22, v23
	v_cvt_pk_bf16_f32 v20, v28, v29
	v_cvt_pk_bf16_f32 v21, v30, v31
	s_waitcnt lgkmcnt(0)
	v_add_f32_e32 v16, v16, v17
	ds_bpermute_b32 v17, v151, v16
	v_lshl_add_u64 v[22:23], v[50:51], 0, s[14:15]
	global_store_dwordx4 v[22:23], v[18:21], off sc1
	s_nop 1
	s_and_saveexec_b64 s[40:41], s[2:3]
	s_cbranch_execz .LBB0_901
	v_lshlrev_b64 v[18:19], 6, v[48:49]
	v_lshl_add_u64 v[18:19], s[38:39], 0, v[18:19]
	s_waitcnt lgkmcnt(0)
	v_add_f32_e32 v16, v16, v17
	global_store_dword v[18:19], v16, off sc1
.LBB0_901:
	s_or_b64 exec, exec, s[40:41]
	v_add_u32_e32 v16, 0xa0, v138
	s_waitcnt lgkmcnt(0)
	v_ashrrev_i32_e32 v17, 31, v16
	v_lshlrev_b64 v[18:19], 11, v[16:17]
	v_lshl_add_u64 v[24:25], v[136:137], 0, v[18:19]
	v_mul_f32_e32 v18, v33, v33
	v_mul_f32_e32 v19, v35, v35
	v_fmac_f32_e32 v18, v32, v32
	v_fmac_f32_e32 v19, v34, v34
	v_add_f32_e32 v18, v18, v19
	v_mul_f32_e32 v19, v41, v41
	v_mul_f32_e32 v20, v43, v43
	v_fmac_f32_e32 v19, v40, v40
	v_fmac_f32_e32 v20, v42, v42
	v_add_f32_e32 v19, v19, v20
	v_add_f32_e32 v22, v18, v19
	v_cvt_pk_bf16_f32 v18, v32, v33
	v_cvt_pk_bf16_f32 v19, v34, v35
	v_cvt_pk_bf16_f32 v20, v40, v41
	v_cvt_pk_bf16_f32 v21, v42, v43
	s_nop 0
	global_store_dwordx4 v[24:25], v[18:21], off sc1
	s_nop 1
	v_mul_f32_e32 v18, v37, v37
	v_mul_f32_e32 v19, v39, v39
	v_fmac_f32_e32 v18, v36, v36
	v_fmac_f32_e32 v19, v38, v38
	v_add_f32_e32 v18, v18, v19
	v_mul_f32_e32 v19, v45, v45
	v_mul_f32_e32 v20, v47, v47
	v_fmac_f32_e32 v19, v44, v44
	v_fmac_f32_e32 v20, v46, v46
	v_add_f32_e32 v19, v19, v20
	v_add_f32_e32 v18, v18, v19
	v_add_f32_e32 v18, v22, v18
	v_mov_b32_e32 v19, v18
	s_nop 1
	v_permlane16_swap_b32_e32 v19, v18
	v_cvt_pk_bf16_f32 v20, v36, v37
	v_cvt_pk_bf16_f32 v21, v38, v39
	v_cvt_pk_bf16_f32 v22, v44, v45
	v_cvt_pk_bf16_f32 v23, v46, v47
	s_waitcnt lgkmcnt(0)
	v_add_f32_e32 v18, v18, v19
	ds_bpermute_b32 v19, v151, v18
	v_lshl_add_u64 v[24:25], v[24:25], 0, s[14:15]
	global_store_dwordx4 v[24:25], v[20:23], off sc1
	s_nop 1
	s_and_saveexec_b64 s[40:41], s[2:3]
	s_cbranch_execz .LBB0_903
	v_lshlrev_b64 v[16:17], 6, v[16:17]
	v_lshl_add_u64 v[16:17], s[38:39], 0, v[16:17]
	s_waitcnt lgkmcnt(0)
	v_add_f32_e32 v18, v18, v19
	global_store_dword v[16:17], v18, off sc1
.LBB0_903:
	s_or_b64 exec, exec, s[40:41]
	v_add_u32_e32 v16, 0xb0, v138
	v_ashrrev_i32_e32 v17, 31, v16
	v_mul_f32_e32 v20, v1, v1
	s_waitcnt lgkmcnt(0)
	v_lshlrev_b64 v[18:19], 11, v[16:17]
	v_fmac_f32_e32 v20, v0, v0
	v_mul_f32_e32 v21, v3, v3
	v_cvt_pk_bf16_f32 v0, v0, v1
	v_cvt_pk_bf16_f32 v1, v2, v3
	v_lshl_add_u64 v[18:19], v[136:137], 0, v[18:19]
	v_fmac_f32_e32 v21, v2, v2
	v_cvt_pk_bf16_f32 v2, v8, v9
	v_cvt_pk_bf16_f32 v3, v10, v11
	v_add_f32_e32 v20, v20, v21
	global_store_dwordx4 v[18:19], v[0:3], off sc1
	s_nop 1
	v_mul_f32_e32 v0, v5, v5
	v_mul_f32_e32 v1, v7, v7
	v_fmac_f32_e32 v0, v4, v4
	v_fmac_f32_e32 v1, v6, v6
	v_mul_f32_e32 v21, v9, v9
	v_mul_f32_e32 v22, v11, v11
	v_add_f32_e32 v0, v0, v1
	v_mul_f32_e32 v1, v13, v13
	v_mul_f32_e32 v2, v15, v15
	v_fmac_f32_e32 v21, v8, v8
	v_fmac_f32_e32 v22, v10, v10
	v_fmac_f32_e32 v1, v12, v12
	v_fmac_f32_e32 v2, v14, v14
	v_add_f32_e32 v21, v21, v22
	v_add_f32_e32 v1, v1, v2
	v_add_f32_e32 v20, v20, v21
	v_add_f32_e32 v0, v0, v1
	v_add_f32_e32 v0, v20, v0
	v_mov_b32_e32 v1, v0
	s_nop 1
	v_permlane16_swap_b32_e32 v1, v0
	v_cvt_pk_bf16_f32 v2, v4, v5
	v_cvt_pk_bf16_f32 v3, v6, v7
	v_cvt_pk_bf16_f32 v4, v12, v13
	v_cvt_pk_bf16_f32 v5, v14, v15
	s_waitcnt lgkmcnt(0)
	v_add_f32_e32 v0, v0, v1
	ds_bpermute_b32 v1, v151, v0
	v_lshl_add_u64 v[6:7], v[18:19], 0, s[14:15]
	global_store_dwordx4 v[6:7], v[2:5], off sc1
	s_nop 1
	s_and_saveexec_b64 s[40:41], s[2:3]
	s_cbranch_execz .LBB0_905
	v_lshlrev_b64 v[2:3], 6, v[16:17]
	v_lshl_add_u64 v[2:3], s[38:39], 0, v[2:3]
	s_waitcnt lgkmcnt(0)
	v_add_f32_e32 v0, v0, v1
	global_store_dword v[2:3], v0, off sc1
